# SSD-B per-head output stage: the 16 x and 3 z loads issued together after the row index (were one or two per s_waitcnt vmcnt(0))
# baseline (speedup 1.0000x reference)
.LBB0_930:
	v_lshl_or_b32 v0, s0, 13, v69
	v_lshl_add_u64 v[106:107], v[0:1], 1, v[72:73]
	v_or_b32_e32 v38, 0x800, v0
	v_mov_b32_e32 v39, v1
	v_or_b32_e32 v42, 0x1000, v0
	v_mov_b32_e32 v43, v1
	global_load_dwordx4 v[34:37], v[106:107], off
	v_lshlrev_b64 v[122:123], 1, v[38:39]
	v_lshlrev_b64 v[126:127], 1, v[42:43]
	v_or_b32_e32 v46, 0x1800, v0
	v_mov_b32_e32 v47, v1
	v_lshl_add_u64 v[38:39], v[72:73], 0, v[122:123]
	v_lshl_add_u64 v[42:43], v[72:73], 0, v[126:127]
	v_lshlrev_b64 v[130:131], 1, v[46:47]
	global_load_dwordx4 v[38:41], v[38:39], off
	v_lshl_add_u64 v[46:47], v[72:73], 0, v[130:131]
	global_load_dwordx4 v[42:45], v[42:43], off
	s_nop 0
	global_load_dwordx4 v[46:49], v[46:47], off
	s_nop 0
	global_load_dwordx4 v[50:53], v[106:107], off offset:64
	v_lshl_add_u64 v[54:55], v[78:79], 0, v[122:123]
	v_lshl_add_u64 v[58:59], v[78:79], 0, v[126:127]
	global_load_dwordx4 v[54:57], v[54:55], off
	v_lshl_add_u64 v[90:91], v[78:79], 0, v[130:131]
	global_load_dwordx4 v[58:61], v[58:59], off
	v_lshl_add_u64 v[98:99], v[80:81], 0, v[122:123]
	v_lshl_add_u64 v[102:103], v[80:81], 0, v[126:127]
	v_lshl_add_u64 v[114:115], v[80:81], 0, v[130:131]
	global_load_dwordx4 v[90:93], v[90:91], off
	s_nop 0
	global_load_dwordx4 v[94:97], v[106:107], off offset:128
	v_add_u32_e32 v110, 4, v110
	global_load_dwordx4 v[98:101], v[98:99], off
	s_waitcnt vmcnt(0) lgkmcnt(0)
	v_mfma_f32_16x16x32_bf16 v[46:49], v[46:49], v[14:17], 0
	global_load_dwordx4 v[102:105], v[102:103], off
	s_nop 0
	global_load_dwordx4 v[114:117], v[114:115], off
	s_nop 0
	global_load_dwordx4 v[118:121], v[106:107], off offset:192
	v_lshl_add_u64 v[106:107], v[82:83], 0, v[122:123]
	global_load_dwordx4 v[122:125], v[106:107], off
	v_lshl_add_u64 v[106:107], v[82:83], 0, v[126:127]
	global_load_dwordx4 v[126:129], v[106:107], off
	v_lshl_add_u64 v[106:107], v[82:83], 0, v[130:131]
	global_load_dwordx4 v[130:133], v[106:107], off
	v_mfma_f32_16x16x32_bf16 v[34:37], v[34:37], v[14:17], 0
	v_mfma_f32_16x16x32_bf16 v[38:41], v[38:41], v[14:17], 0
	v_mfma_f32_16x16x32_bf16 v[42:45], v[42:45], v[14:17], 0
	v_mfma_f32_16x16x32_bf16 v[46:49], v[90:93], v[10:13], v[46:49]
	v_mfma_f32_16x16x32_bf16 v[34:37], v[50:53], v[10:13], v[34:37]
	v_mul_f32_e32 v50, 0x3fb8aa3b, v88
	v_exp_f32_e32 v50, v50
	v_mfma_f32_16x16x32_bf16 v[38:41], v[54:57], v[10:13], v[38:41]
	v_mfma_f32_16x16x32_bf16 v[42:45], v[58:61], v[10:13], v[42:45]
	s_waitcnt vmcnt(0) lgkmcnt(0)
	v_mfma_f32_16x16x32_bf16 v[46:49], v[114:117], v[6:9], v[46:49]
	v_mfma_f32_16x16x32_bf16 v[34:37], v[94:97], v[6:9], v[34:37]
	v_mfma_f32_16x16x32_bf16 v[38:41], v[98:101], v[6:9], v[38:41]
	v_mfma_f32_16x16x32_bf16 v[42:45], v[102:105], v[6:9], v[42:45]
	v_mfma_f32_16x16x32_bf16 v[46:49], v[130:133], v[2:5], v[46:49]
	v_mfma_f32_16x16x32_bf16 v[34:37], v[118:121], v[2:5], v[34:37]
	v_mfma_f32_16x16x32_bf16 v[38:41], v[122:125], v[2:5], v[38:41]
	s_nop 5
	v_fma_f32 v104, v50, v46, v18
	v_fma_f32 v105, v50, v47, v19
	v_add_u32_e32 v18, 0x8000, v0
	v_mov_b32_e32 v19, v1
	v_mfma_f32_16x16x32_bf16 v[42:45], v[126:129], v[2:5], v[42:45]
	v_lshlrev_b64 v[46:47], 1, v[18:19]
	v_pk_fma_f32 v[92:93], v[50:51], v[34:35], v[30:31] op_sel_hi:[0,1,1]
	v_lshl_add_u64 v[18:19], v[72:73], 0, v[46:47]
	v_lshl_add_u64 v[30:31], v[80:81], 0, v[46:47]
	v_pk_fma_f32 v[90:91], v[50:51], v[36:37], v[32:33] op_sel_hi:[0,1,1]
	global_load_dwordx4 v[114:117], v[18:19], off
	v_pk_fma_f32 v[94:95], v[50:51], v[40:41], v[28:29] op_sel_hi:[0,1,1]
	global_load_dwordx4 v[30:33], v[30:31], off
	v_add_u32_e32 v18, 0x8800, v0
	v_mov_b32_e32 v19, v1
	v_pk_fma_f32 v[96:97], v[50:51], v[38:39], v[26:27] op_sel_hi:[0,1,1]
	v_pk_fma_f32 v[98:99], v[50:51], v[44:45], v[24:25] op_sel_hi:[0,1,1]
	v_pk_fma_f32 v[100:101], v[50:51], v[42:43], v[22:23] op_sel_hi:[0,1,1]
	v_pk_fma_f32 v[102:103], v[50:51], v[48:49], v[20:21] op_sel_hi:[0,1,1]
	v_lshlrev_b64 v[50:51], 1, v[18:19]
	v_lshl_add_u64 v[18:19], v[72:73], 0, v[50:51]
	v_lshl_add_u64 v[34:35], v[80:81], 0, v[50:51]
	global_load_dwordx4 v[118:121], v[18:19], off
	s_waitcnt vmcnt(0) lgkmcnt(0)
	v_mfma_f32_16x16x32_bf16 v[114:117], v[114:117], v[14:17], 0
	global_load_dwordx4 v[34:37], v[34:35], off
	v_add_u32_e32 v18, 0x9000, v0
	v_mov_b32_e32 v19, v1
	v_lshlrev_b64 v[54:55], 1, v[18:19]
	v_add_u32_e32 v0, 0x9800, v0
	v_lshl_add_u64 v[18:19], v[72:73], 0, v[54:55]
	v_lshlrev_b64 v[58:59], 1, v[0:1]
	v_lshl_add_u64 v[22:23], v[78:79], 0, v[54:55]
	global_load_dwordx4 v[122:125], v[18:19], off
	v_lshl_add_u64 v[26:27], v[78:79], 0, v[58:59]
	global_load_dwordx4 v[22:25], v[22:23], off
	v_lshl_add_u64 v[18:19], v[72:73], 0, v[58:59]
	global_load_dwordx4 v[126:129], v[18:19], off
	v_lshl_add_u64 v[38:39], v[80:81], 0, v[54:55]
	global_load_dwordx4 v[26:29], v[26:27], off
	v_lshl_add_u64 v[18:19], v[78:79], 0, v[46:47]
	global_load_dwordx4 v[130:133], v[18:19], off
	v_lshl_add_u64 v[42:43], v[80:81], 0, v[58:59]
	global_load_dwordx4 v[38:41], v[38:39], off
	v_lshl_add_u64 v[18:19], v[78:79], 0, v[50:51]
	global_load_dwordx4 v[18:21], v[18:19], off
	v_lshl_add_u64 v[46:47], v[82:83], 0, v[46:47]
	global_load_dwordx4 v[42:45], v[42:43], off
	v_lshl_add_u64 v[50:51], v[82:83], 0, v[50:51]
	v_lshl_add_u64 v[54:55], v[82:83], 0, v[54:55]
	v_lshl_add_u64 v[58:59], v[82:83], 0, v[58:59]
	global_load_dwordx4 v[46:49], v[46:47], off
	v_mfma_f32_16x16x32_bf16 v[118:121], v[118:121], v[14:17], 0
	global_load_dwordx4 v[50:53], v[50:51], off
	v_mul_f32_e32 v0, 0x3fb8aa3b, v89
	global_load_dwordx4 v[54:57], v[54:55], off
	s_waitcnt vmcnt(0) lgkmcnt(0)
	v_mfma_f32_16x16x32_bf16 v[122:125], v[122:125], v[14:17], 0
	global_load_dwordx4 v[58:61], v[58:59], off
	v_exp_f32_e32 v0, v0
	v_mfma_f32_16x16x32_bf16 v[14:17], v[126:129], v[14:17], 0
	v_mfma_f32_16x16x32_bf16 v[114:117], v[130:133], v[10:13], v[114:117]
	v_mfma_f32_16x16x32_bf16 v[18:21], v[18:21], v[10:13], v[118:121]
	v_mfma_f32_16x16x32_bf16 v[22:25], v[22:25], v[10:13], v[122:125]
	v_mfma_f32_16x16x32_bf16 v[10:13], v[26:29], v[10:13], v[14:17]
	v_mfma_f32_16x16x32_bf16 v[14:17], v[30:33], v[6:9], v[114:117]
	v_mfma_f32_16x16x32_bf16 v[18:21], v[34:37], v[6:9], v[18:21]
	v_mfma_f32_16x16x32_bf16 v[22:25], v[38:41], v[6:9], v[22:25]
	v_mfma_f32_16x16x32_bf16 v[6:9], v[42:45], v[6:9], v[10:13]
	v_mfma_f32_16x16x32_bf16 v[10:13], v[46:49], v[2:5], v[14:17]
	v_mfma_f32_16x16x32_bf16 v[14:17], v[50:53], v[2:5], v[18:21]
	v_mfma_f32_16x16x32_bf16 v[24:27], v[54:57], v[2:5], v[22:25]
	s_waitcnt vmcnt(0) lgkmcnt(0)
	v_mfma_f32_16x16x32_bf16 v[6:9], v[58:61], v[2:5], v[6:9]
	s_nop 3
	v_fma_f32 v4, v0, v12, v90
	v_fma_f32 v5, v0, v13, v91
	v_pk_fma_f32 v[2:3], v[0:1], v[10:11], v[92:93] op_sel_hi:[0,1,1]
	v_pk_fma_f32 v[20:21], v[0:1], v[16:17], v[94:95] op_sel_hi:[0,1,1]
	v_pk_fma_f32 v[22:23], v[0:1], v[14:15], v[96:97] op_sel_hi:[0,1,1]
	v_pk_fma_f32 v[14:15], v[0:1], v[26:27], v[98:99] op_sel_hi:[0,1,1]
	v_pk_fma_f32 v[18:19], v[0:1], v[24:25], v[100:101] op_sel_hi:[0,1,1]
	v_pk_fma_f32 v[8:9], v[0:1], v[8:9], v[102:103] op_sel_hi:[0,1,1]
	v_pk_fma_f32 v[6:7], v[0:1], v[6:7], v[104:105] op_sel_hi:[0,1,1]
	v_mov_b32_e32 v0, s64
	v_mov_b32_e32 v10, s65
	s_nop 0
	v_readfirstlane_b32 s4, v0
	v_readfirstlane_b32 s5, v10
	s_nop 0
	v_mov_b32_e32 v10, s4
	v_mov_b32_e32 v11, s5
	global_load_dwordx2 v[10:11], v[10:11], off offset:168
	v_readlane_b32 s4, v254, 51
	s_add_i32 s4, s0, s4
	s_ashr_i32 s5, s4, 31
	s_lshl_b64 s[4:5], s[4:5], 2
	s_waitcnt vmcnt(0) lgkmcnt(0)
	v_mov_b32_e32 v0, v11
	s_nop 0
	v_readfirstlane_b32 s12, v10
	v_readfirstlane_b32 s13, v0
	s_add_u32 s4, s12, s4
	s_addc_u32 s5, s13, s5
	s_lshl_b32 s18, s1, 1
	v_lshl_add_u64 v[16:17], v[74:75], 0, s[18:19]
	global_load_dwordx2 v[12:13], v[16:17], off
	global_load_dwordx2 v[186:187], v[16:17], off offset:32
	global_load_dwordx2 v[188:189], v[16:17], off offset:64
	global_load_dwordx2 v[190:191], v[16:17], off offset:96
	v_or_b32_e32 v0, s1, v109
	v_mul_lo_u32 v0, v0, s82
	v_lshl_add_u64 v[192:193], v[0:1], 1, v[76:77]
	global_load_ushort v168, v[192:193], off
	v_add_co_u32_e32 v194, vcc, s33, v192
	s_nop 1
	v_addc_co_u32_e32 v195, vcc, 0, v193, vcc
	global_load_ushort v169, v[194:195], off
	v_add_co_u32_e32 v194, vcc, s46, v192
	s_nop 1
	v_addc_co_u32_e32 v195, vcc, 0, v193, vcc
	global_load_ushort v170, v[194:195], off
	v_add_co_u32_e32 v194, vcc, s47, v192
	s_nop 1
	v_addc_co_u32_e32 v195, vcc, 0, v193, vcc
	global_load_ushort v171, v[194:195], off
	v_add_co_u32_e32 v194, vcc, s44, v192
	s_nop 1
	v_addc_co_u32_e32 v195, vcc, 0, v193, vcc
	global_load_ushort v172, v[194:195], off
	v_add_co_u32_e32 v194, vcc, s48, v192
	s_nop 1
	v_addc_co_u32_e32 v195, vcc, 0, v193, vcc
	global_load_ushort v173, v[194:195], off
	v_add_co_u32_e32 v194, vcc, s49, v192
	s_nop 1
	v_addc_co_u32_e32 v195, vcc, 0, v193, vcc
	global_load_ushort v174, v[194:195], off
	v_add_co_u32_e32 v194, vcc, s50, v192
	s_nop 1
	v_addc_co_u32_e32 v195, vcc, 0, v193, vcc
	global_load_ushort v175, v[194:195], off
	v_add_co_u32_e32 v194, vcc, s35, v192
	s_nop 1
	v_addc_co_u32_e32 v195, vcc, 0, v193, vcc
	global_load_ushort v176, v[194:195], off
	v_add_co_u32_e32 v194, vcc, s51, v192
	s_nop 1
	v_addc_co_u32_e32 v195, vcc, 0, v193, vcc
	global_load_ushort v177, v[194:195], off
	v_add_co_u32_e32 v194, vcc, s52, v192
	s_nop 1
	v_addc_co_u32_e32 v195, vcc, 0, v193, vcc
	global_load_ushort v178, v[194:195], off
	v_add_co_u32_e32 v194, vcc, s53, v192
	s_nop 1
	v_addc_co_u32_e32 v195, vcc, 0, v193, vcc
	global_load_ushort v179, v[194:195], off
	v_add_co_u32_e32 v194, vcc, s54, v192
	s_nop 1
	v_addc_co_u32_e32 v195, vcc, 0, v193, vcc
	global_load_ushort v180, v[194:195], off
	v_add_co_u32_e32 v194, vcc, s55, v192
	s_nop 1
	v_addc_co_u32_e32 v195, vcc, 0, v193, vcc
	global_load_ushort v181, v[194:195], off
	v_add_co_u32_e32 v194, vcc, s56, v192
	s_nop 1
	v_addc_co_u32_e32 v195, vcc, 0, v193, vcc
	global_load_ushort v182, v[194:195], off
	v_add_co_u32_e32 v194, vcc, s57, v192
	s_nop 1
	v_addc_co_u32_e32 v195, vcc, 0, v193, vcc
	global_load_ushort v183, v[194:195], off
	v_mov_b64_e32 v[10:11], s[4:5]
	global_load_dword v10, v[10:11], off
	v_lshl_add_u32 v11, s0, 15, v65
	s_add_i32 s0, s0, 1
	s_add_u32 s8, s8, 64
	s_addc_u32 s9, s9, 0
	s_mov_b64 s[4:5], 0x240000
	v_lshl_add_u64 v[86:87], v[86:87], 0, s[4:5]
	s_cmp_eq_u32 s0, 4
	s_waitcnt vmcnt(0) lgkmcnt(0)
	v_lshlrev_b32_e32 v24, 16, v12
	v_and_b32_e32 v25, 0xffff0000, v12
	v_lshlrev_b32_e32 v26, 16, v13
	v_and_b32_e32 v27, 0xffff0000, v13
	v_lshl_add_u64 v[12:13], v[0:1], 1, v[76:77]
	v_mul_f32_e32 v28, 0xbfb8aa3b, v24
	v_exp_f32_e32 v28, v28
	s_waitcnt lgkmcnt(0)
	v_lshlrev_b32_e32 v30, 16, v168
	v_mul_f32_e32 v0, 0xbfb8aa3b, v25
	v_exp_f32_e32 v0, v0
	v_add_f32_e32 v28, 1.0, v28
	v_rcp_f32_e32 v28, v28
	v_add_f32_e32 v0, 1.0, v0
	v_lshlrev_b32_e32 v31, 16, v169
	v_rcp_f32_e32 v29, v0
	v_pk_fma_f32 v[2:3], v[10:11], v[30:31], v[2:3] op_sel_hi:[0, 1, 1]
	v_pk_mul_f32 v[24:25], v[28:29], v[24:25]
	s_nop 0
	v_pk_mul_f32 v[2:3], v[2:3], v[24:25]
	s_waitcnt lgkmcnt(0)
	v_lshlrev_b32_e32 v28, 16, v170
	v_mul_f32_e32 v24, 0xbfb8aa3b, v26
	v_mul_f32_e32 v0, 0xbfb8aa3b, v27
	v_exp_f32_e32 v24, v24
	v_exp_f32_e32 v0, v0
	v_add_f32_e32 v24, 1.0, v24
	v_add_f32_e32 v0, 1.0, v0
	v_rcp_f32_e32 v24, v24
	s_waitcnt lgkmcnt(0)
	v_lshlrev_b32_e32 v29, 16, v171
	v_rcp_f32_e32 v25, v0
	v_pk_fma_f32 v[4:5], v[10:11], v[28:29], v[4:5] op_sel_hi:[0, 1, 1]
	v_pk_mul_f32 v[24:25], v[24:25], v[26:27]
	s_nop 0
	v_pk_mul_f32 v[4:5], v[24:25], v[4:5]
	ds_write_b128 v11, v[2:5]
	s_waitcnt lgkmcnt(0)
	v_lshlrev_b32_e32 v26, 16, v186
	v_and_b32_e32 v27, 0xffff0000, v186
	v_mul_f32_e32 v28, 0xbfb8aa3b, v26
	v_lshlrev_b32_e32 v30, 16, v172
	v_mul_f32_e32 v0, 0xbfb8aa3b, v27
	v_exp_f32_e32 v28, v28
	v_exp_f32_e32 v0, v0
	v_lshlrev_b32_e32 v24, 16, v187
	v_and_b32_e32 v25, 0xffff0000, v187
	v_add_f32_e32 v28, 1.0, v28
	v_add_f32_e32 v0, 1.0, v0
	v_rcp_f32_e32 v28, v28
	s_waitcnt lgkmcnt(0)
	v_lshlrev_b32_e32 v31, 16, v173
	v_rcp_f32_e32 v29, v0
	v_pk_fma_f32 v[22:23], v[10:11], v[30:31], v[22:23] op_sel_hi:[0, 1, 1]
	v_pk_mul_f32 v[26:27], v[28:29], v[26:27]
	s_nop 0
	v_pk_mul_f32 v[22:23], v[22:23], v[26:27]
	s_waitcnt lgkmcnt(0)
	v_lshlrev_b32_e32 v28, 16, v174
	v_mul_f32_e32 v26, 0xbfb8aa3b, v24
	v_mul_f32_e32 v0, 0xbfb8aa3b, v25
	v_exp_f32_e32 v26, v26
	v_exp_f32_e32 v0, v0
	v_add_f32_e32 v26, 1.0, v26
	v_add_f32_e32 v0, 1.0, v0
	v_rcp_f32_e32 v26, v26
	s_waitcnt lgkmcnt(0)
	v_lshlrev_b32_e32 v29, 16, v175
	v_rcp_f32_e32 v27, v0
	v_pk_fma_f32 v[20:21], v[10:11], v[28:29], v[20:21] op_sel_hi:[0, 1, 1]
	v_pk_mul_f32 v[24:25], v[26:27], v[24:25]
	s_nop 0
	v_pk_mul_f32 v[24:25], v[24:25], v[20:21]
	v_mov_b32_e32 v20, v2
	v_mov_b32_e32 v2, v3
	v_mov_b32_e32 v3, v23
	v_mov_b32_e32 v21, v22
	v_pk_mul_f32 v[2:3], v[2:3], v[2:3]
	ds_write_b128 v11, v[22:25] offset:1024
	v_pk_fma_f32 v[2:3], v[20:21], v[20:21], v[2:3]
	v_mov_b32_e32 v20, v4
	v_mov_b32_e32 v21, v24
	v_pk_fma_f32 v[2:3], v[20:21], v[20:21], v[2:3]
	v_mov_b32_e32 v4, v5
	v_mov_b32_e32 v5, v25
	v_pk_fma_f32 v[2:3], v[4:5], v[4:5], v[2:3]
	s_nop 0
	v_add_f32_e32 v0, v113, v2
	v_add_f32_e32 v0, v0, v3
	s_waitcnt lgkmcnt(0)
	v_lshlrev_b32_e32 v20, 16, v188
	v_and_b32_e32 v21, 0xffff0000, v188
	v_lshlrev_b32_e32 v4, 16, v189
	v_and_b32_e32 v5, 0xffff0000, v189
	s_waitcnt lgkmcnt(0)
	v_lshlrev_b32_e32 v22, 16, v176
	v_mul_f32_e32 v2, 0xbfb8aa3b, v20
	v_exp_f32_e32 v2, v2
	s_waitcnt lgkmcnt(0)
	v_lshlrev_b32_e32 v23, 16, v177
	v_mul_f32_e32 v3, 0xbfb8aa3b, v21
	v_exp_f32_e32 v3, v3
	v_add_f32_e32 v2, 1.0, v2
	v_rcp_f32_e32 v2, v2
	v_pk_fma_f32 v[18:19], v[10:11], v[22:23], v[18:19] op_sel_hi:[0, 1, 1]
	v_add_f32_e32 v3, 1.0, v3
	v_rcp_f32_e32 v3, v3
	s_nop 0
	v_pk_mul_f32 v[2:3], v[2:3], v[20:21]
	s_nop 0
	v_pk_mul_f32 v[2:3], v[18:19], v[2:3]
	s_waitcnt lgkmcnt(0)
	v_lshlrev_b32_e32 v20, 16, v178
	v_mul_f32_e32 v18, 0xbfb8aa3b, v4
	v_exp_f32_e32 v18, v18
	s_waitcnt lgkmcnt(0)
	v_lshlrev_b32_e32 v21, 16, v179
	v_mul_f32_e32 v19, 0xbfb8aa3b, v5
	v_exp_f32_e32 v19, v19
	v_add_f32_e32 v18, 1.0, v18
	v_rcp_f32_e32 v18, v18
	v_pk_fma_f32 v[14:15], v[10:11], v[20:21], v[14:15] op_sel_hi:[0, 1, 1]
	v_add_f32_e32 v19, 1.0, v19
	v_rcp_f32_e32 v19, v19
	s_nop 0
	v_pk_mul_f32 v[4:5], v[18:19], v[4:5]
	s_nop 0
	v_pk_mul_f32 v[4:5], v[4:5], v[14:15]
	ds_write_b128 v11, v[2:5] offset:2048
	s_nop 0
	s_nop 0
	s_waitcnt lgkmcnt(0)
	v_lshlrev_b32_e32 v20, 16, v180
	v_lshlrev_b32_e32 v16, 16, v190
	v_and_b32_e32 v17, 0xffff0000, v190
	v_mul_f32_e32 v18, 0xbfb8aa3b, v16
	v_lshlrev_b32_e32 v21, 16, v181
	v_mul_f32_e32 v19, 0xbfb8aa3b, v17
	v_exp_f32_e32 v18, v18
	v_exp_f32_e32 v19, v19
	v_pk_fma_f32 v[6:7], v[10:11], v[20:21], v[6:7] op_sel_hi:[0, 1, 1]
	v_lshlrev_b32_e32 v14, 16, v191
	v_add_f32_e32 v18, 1.0, v18
	v_add_f32_e32 v19, 1.0, v19
	v_rcp_f32_e32 v18, v18
	v_rcp_f32_e32 v19, v19
	v_and_b32_e32 v15, 0xffff0000, v191
	v_pk_mul_f32 v[16:17], v[18:19], v[16:17]
	s_nop 0
	v_pk_mul_f32 v[6:7], v[6:7], v[16:17]
	s_nop 0
	v_mul_f32_e32 v12, 0xbfb8aa3b, v14
	v_exp_f32_e32 v12, v12
	s_waitcnt lgkmcnt(0)
	v_lshlrev_b32_e32 v16, 16, v182
	v_add_f32_e32 v12, 1.0, v12
	v_rcp_f32_e32 v12, v12
	v_lshlrev_b32_e32 v17, 16, v183
	v_pk_fma_f32 v[8:9], v[10:11], v[16:17], v[8:9] op_sel_hi:[0, 1, 1]
	v_mul_f32_e32 v10, 0xbfb8aa3b, v15
	v_exp_f32_e32 v10, v10
	s_nop 0
	v_add_f32_e32 v10, 1.0, v10
	v_rcp_f32_e32 v13, v10
	s_nop 0
	v_pk_mul_f32 v[12:13], v[12:13], v[14:15]
	s_nop 0
	v_pk_mul_f32 v[8:9], v[12:13], v[8:9]
	v_mov_b32_e32 v12, v2
	v_mov_b32_e32 v2, v3
	v_mov_b32_e32 v3, v7
	v_mov_b32_e32 v13, v6
	v_pk_mul_f32 v[2:3], v[2:3], v[2:3]
	ds_write_b128 v11, v[6:9] offset:3072
	v_pk_fma_f32 v[2:3], v[12:13], v[12:13], v[2:3]
	v_mov_b32_e32 v12, v4
	v_mov_b32_e32 v13, v8
	v_pk_fma_f32 v[2:3], v[12:13], v[12:13], v[2:3]
	v_mov_b32_e32 v4, v5
	v_mov_b32_e32 v5, v9
	v_pk_fma_f32 v[2:3], v[4:5], v[4:5], v[2:3]
	s_nop 0
	v_add_f32_e32 v0, v0, v2
	v_add_f32_e32 v113, v0, v3
	s_cbranch_scc1 .LBB0_965
